# v36 + fold remaining canonicalize pairs in W1 relu2 epilogue (v_max(0,x) only)
# baseline (speedup 1.0000x reference)
; __device__ __forceinline__ u32x4 pk8(f32x4 a, f32x4 b) { u32x4 r; r.x = pk2(a[0], a[1]); r.y = pk2(a[2], a[3]); r.z = pk2(b[0], b[1]); r.w = pk2(b[2], b[3]); return r; }
; #define GEMM_CALL(EPI, gA, gB, gM, gN, gK, gLDA, gLDB, cshift, Eobj) do { \
;         pg8::Gemm gg__{(gA), (gB), (gM), (gN), (gK), (gLDA), (gLDB)}; pg8::StaticOrder so__; so__.init((gM), (gN), G, (int)((blockIdx.x + G - ((cshift) % G)) % G)); \
;         pg8::gemm_phase<EPI, pg8::StaticOrder, true, true>(lds, gg__, so__, (Eobj)); } while (0)
;     __device__ __forceinline__ void operator()(AccRef acc, const pg8::Unit& u, int wr, int wc, int fr, int fq) const {
;         bf16_t* base = O + (size_t)(u.pm * 256 + wr * 64 + fr) * ldc + u.pn * 256 + wc * 32 + 8 * fq;
; #pragma unroll
;         for (int ai = 0; ai < 2; ++ai)
; #pragma unroll
;             for (int m = 0; m < 4; ++m) { bf16_t* rowp = base + (size_t)(ai * 128 + m * 16) * ldc;
; #pragma unroll
;                 for (int bj = 0; bj < 2; ++bj) { f32x4 v0 = acc[ai][bj][m][0], v1 = acc[ai][bj][m][1];
; #pragma unroll
;                     for (int j = 0; j < 4; ++j) { float a = fmaxf(v0[j], 0.f), b = fmaxf(v1[j], 0.f); v0[j] = a * a; v1[j] = b * b; }
;                     *(u32x4*)(rowp + bj * 128) = pk8(v0, v1); } }
;     }
; __global__ void __launch_bounds__(512, 2) fwd_megakernel(Args a) {
;     ...
;         { EpiRelu2 E{BIG, DFF}; GEMM_CALL(EpiRelu2, H, W1T + (size_t)l * D * DFF, nrows, DFF, 1024, 1024, 1024, 0, E); }
.LBB0_1629:
	v_mov_b32_e32 v138, v140
	v_mov_b32_e32 v144, v141
	s_lshl_b32 s53, s84, 8
	s_add_i32 s53, s53, s17
	v_add_u32_e32 v138, s53, v138
	v_ashrrev_i32_e32 v139, 31, v138
	v_lshlrev_b64 v[138:139], 13, v[138:139]
	s_lshl_b32 s58, s82, 8
	v_lshl_add_u64 v[138:139], s[30:31], 0, v[138:139]
	s_ashr_i32 s59, s58, 31
	v_lshl_add_u64 v[138:139], s[58:59], 1, v[138:139]
	s_mov_b32 s53, s60
	v_lshlrev_b32_e32 v144, 3, v144
	v_max_f32_e32 v120, 0, v120
	v_max_f32_e32 v124, 0, v124
	v_max_f32_e32 v121, 0, v121
	v_max_f32_e32 v125, 0, v125
	v_max_f32_e32 v122, 0, v122
	v_max_f32_e32 v126, 0, v126
	v_max_f32_e32 v123, 0, v123
	v_max_f32_e32 v127, 0, v127
	v_lshl_add_u64 v[138:139], v[138:139], 0, s[52:53]
	v_ashrrev_i32_e32 v145, 31, v144
	v_pk_mul_f32 v[120:121], v[120:121], v[120:121]
	v_pk_mul_f32 v[124:125], v[124:125], v[124:125]
	v_pk_mul_f32 v[122:123], v[122:123], v[122:123]
	v_pk_mul_f32 v[126:127], v[126:127], v[126:127]
	v_lshl_add_u64 v[138:139], v[144:145], 1, v[138:139]
	v_cvt_pk_bf16_f32 v120, v120, v121
	v_cvt_pk_bf16_f32 v121, v122, v123
	v_cvt_pk_bf16_f32 v122, v124, v125
	v_cvt_pk_bf16_f32 v123, v126, v127
	v_max_f32_e32 v112, 0, v112
	v_max_f32_e32 v113, 0, v113
	global_store_dwordx4 v[138:139], v[120:123], off
	s_nop 1
	v_pk_mul_f32 v[120:121], v[112:113], v[112:113]
	v_max_f32_e32 v114, 0, v114
	v_max_f32_e32 v116, 0, v116
	v_max_f32_e32 v117, 0, v117
	v_max_f32_e32 v112, 0, v118
	v_max_f32_e32 v113, 0, v119
	v_max_f32_e32 v115, 0, v115
	v_pk_mul_f32 v[116:117], v[116:117], v[116:117]
	v_pk_mul_f32 v[118:119], v[112:113], v[112:113]
	v_pk_mul_f32 v[122:123], v[114:115], v[114:115]
	v_cvt_pk_bf16_f32 v112, v116, v117
	v_cvt_pk_bf16_f32 v113, v118, v119
	v_cvt_pk_bf16_f32 v114, v120, v121
	v_cvt_pk_bf16_f32 v115, v122, v123
	v_max_f32_e32 v104, 0, v104
	v_max_f32_e32 v105, 0, v105
	global_store_dwordx4 v[138:139], v[112:115], off offset:256
	s_nop 1
	v_pk_mul_f32 v[112:113], v[104:105], v[104:105]
	v_max_f32_e32 v108, 0, v108
	v_max_f32_e32 v109, 0, v109
	v_max_f32_e32 v106, 0, v106
	v_pk_mul_f32 v[108:109], v[108:109], v[108:109]
	v_max_f32_e32 v104, 0, v110
	v_max_f32_e32 v105, 0, v111
	v_max_f32_e32 v107, 0, v107
	v_pk_mul_f32 v[110:111], v[104:105], v[104:105]
	v_pk_mul_f32 v[114:115], v[106:107], v[106:107]
	v_cvt_pk_bf16_f32 v104, v108, v109
	v_add_co_u32_e32 v108, vcc, s1, v138
	v_cvt_pk_bf16_f32 v105, v110, v111
	v_cvt_pk_bf16_f32 v106, v112, v113
	v_cvt_pk_bf16_f32 v107, v114, v115
	v_addc_co_u32_e32 v109, vcc, 0, v139, vcc
	v_max_f32_e32 v96, 0, v96
	v_max_f32_e32 v97, 0, v97
	global_store_dwordx4 v[108:109], v[104:107], off
	s_nop 1
	v_pk_mul_f32 v[104:105], v[96:97], v[96:97]
	v_max_f32_e32 v98, 0, v98
	v_max_f32_e32 v100, 0, v100
	v_max_f32_e32 v101, 0, v101
	v_max_f32_e32 v96, 0, v102
	v_max_f32_e32 v97, 0, v103
	v_max_f32_e32 v99, 0, v99
	v_pk_mul_f32 v[100:101], v[100:101], v[100:101]
	v_pk_mul_f32 v[102:103], v[96:97], v[96:97]
	v_pk_mul_f32 v[106:107], v[98:99], v[98:99]
	v_cvt_pk_bf16_f32 v96, v100, v101
	v_cvt_pk_bf16_f32 v97, v102, v103
	v_cvt_pk_bf16_f32 v98, v104, v105
	v_cvt_pk_bf16_f32 v99, v106, v107
	v_max_f32_e32 v88, 0, v88
	v_max_f32_e32 v89, 0, v89
	global_store_dwordx4 v[108:109], v[96:99], off offset:256
	s_nop 1
	v_pk_mul_f32 v[96:97], v[88:89], v[88:89]
	v_max_f32_e32 v92, 0, v92
	v_max_f32_e32 v93, 0, v93
	v_max_f32_e32 v90, 0, v90
	v_pk_mul_f32 v[92:93], v[92:93], v[92:93]
	v_max_f32_e32 v88, 0, v94
	v_max_f32_e32 v89, 0, v95
	v_max_f32_e32 v91, 0, v91
	s_mov_b32 s53, 0x40000
	v_pk_mul_f32 v[94:95], v[88:89], v[88:89]
	v_pk_mul_f32 v[98:99], v[90:91], v[90:91]
	v_cvt_pk_bf16_f32 v88, v92, v93
	v_add_co_u32_e32 v92, vcc, s53, v138
	v_cvt_pk_bf16_f32 v89, v94, v95
	v_cvt_pk_bf16_f32 v90, v96, v97
	v_cvt_pk_bf16_f32 v91, v98, v99
	v_addc_co_u32_e32 v93, vcc, 0, v139, vcc
	v_max_f32_e32 v80, 0, v80
	v_max_f32_e32 v81, 0, v81
	global_store_dwordx4 v[92:93], v[88:91], off
	s_nop 1
	v_pk_mul_f32 v[88:89], v[80:81], v[80:81]
	v_max_f32_e32 v82, 0, v82
	v_max_f32_e32 v84, 0, v84
	v_max_f32_e32 v85, 0, v85
	v_max_f32_e32 v80, 0, v86
	v_max_f32_e32 v81, 0, v87
	v_max_f32_e32 v83, 0, v83
	v_pk_mul_f32 v[84:85], v[84:85], v[84:85]
	v_pk_mul_f32 v[86:87], v[80:81], v[80:81]
	v_pk_mul_f32 v[90:91], v[82:83], v[82:83]
	v_cvt_pk_bf16_f32 v80, v84, v85
	v_cvt_pk_bf16_f32 v81, v86, v87
	v_cvt_pk_bf16_f32 v82, v88, v89
	v_cvt_pk_bf16_f32 v83, v90, v91
	v_max_f32_e32 v72, 0, v72
	v_max_f32_e32 v73, 0, v73
	global_store_dwordx4 v[92:93], v[80:83], off offset:256
	s_nop 1
	v_pk_mul_f32 v[80:81], v[72:73], v[72:73]
	v_max_f32_e32 v76, 0, v76
	v_max_f32_e32 v77, 0, v77
	v_max_f32_e32 v74, 0, v74
	v_pk_mul_f32 v[76:77], v[76:77], v[76:77]
	v_max_f32_e32 v72, 0, v78
	v_max_f32_e32 v73, 0, v79
	v_max_f32_e32 v75, 0, v75
	s_mov_b32 s53, 0x60000
	v_pk_mul_f32 v[78:79], v[72:73], v[72:73]
	v_pk_mul_f32 v[82:83], v[74:75], v[74:75]
	v_cvt_pk_bf16_f32 v72, v76, v77
	v_add_co_u32_e32 v76, vcc, s53, v138
	v_cvt_pk_bf16_f32 v73, v78, v79
	v_cvt_pk_bf16_f32 v74, v80, v81
	v_cvt_pk_bf16_f32 v75, v82, v83
	v_addc_co_u32_e32 v77, vcc, 0, v139, vcc
	v_max_f32_e32 v64, 0, v64
	v_max_f32_e32 v65, 0, v65
	global_store_dwordx4 v[76:77], v[72:75], off
	s_nop 1
	v_pk_mul_f32 v[72:73], v[64:65], v[64:65]
	v_max_f32_e32 v66, 0, v66
	v_max_f32_e32 v68, 0, v68
	v_max_f32_e32 v69, 0, v69
	v_max_f32_e32 v64, 0, v70
	v_max_f32_e32 v65, 0, v71
	v_max_f32_e32 v67, 0, v67
	v_pk_mul_f32 v[68:69], v[68:69], v[68:69]
; __device__ __forceinline__ u32x4 pk8(f32x4 a, f32x4 b) { u32x4 r; r.x = pk2(a[0], a[1]); r.y = pk2(a[2], a[3]); r.z = pk2(b[0], b[1]); r.w = pk2(b[2], b[3]); return r; }
; #define GEMM_CALL(EPI, gA, gB, gM, gN, gK, gLDA, gLDB, cshift, Eobj) do { \
;         pg8::Gemm gg__{(gA), (gB), (gM), (gN), (gK), (gLDA), (gLDB)}; pg8::StaticOrder so__; so__.init((gM), (gN), G, (int)((blockIdx.x + G - ((cshift) % G)) % G)); \
;         pg8::gemm_phase<EPI, pg8::StaticOrder, true, true>(lds, gg__, so__, (Eobj)); } while (0)
;     __device__ __forceinline__ void operator()(AccRef acc, const pg8::Unit& u, int wr, int wc, int fr, int fq) const {
;         bf16_t* base = O + (size_t)(u.pm * 256 + wr * 64 + fr) * ldc + u.pn * 256 + wc * 32 + 8 * fq;
; #pragma unroll
;         for (int ai = 0; ai < 2; ++ai)
; #pragma unroll
;             for (int m = 0; m < 4; ++m) { bf16_t* rowp = base + (size_t)(ai * 128 + m * 16) * ldc;
; #pragma unroll
;                 for (int bj = 0; bj < 2; ++bj) { f32x4 v0 = acc[ai][bj][m][0], v1 = acc[ai][bj][m][1];
; #pragma unroll
;                     for (int j = 0; j < 4; ++j) { float a = fmaxf(v0[j], 0.f), b = fmaxf(v1[j], 0.f); v0[j] = a * a; v1[j] = b * b; }
;                     *(u32x4*)(rowp + bj * 128) = pk8(v0, v1); } }
;     }
; __global__ void __launch_bounds__(512, 2) fwd_megakernel(Args a) {
;     ...
;         { EpiRelu2 E{BIG, DFF}; GEMM_CALL(EpiRelu2, H, W1T + (size_t)l * D * DFF, nrows, DFF, 1024, 1024, 1024, 0, E); }
	v_pk_mul_f32 v[70:71], v[64:65], v[64:65]
	v_pk_mul_f32 v[74:75], v[66:67], v[66:67]
	v_cvt_pk_bf16_f32 v64, v68, v69
	v_cvt_pk_bf16_f32 v65, v70, v71
	v_cvt_pk_bf16_f32 v66, v72, v73
	v_cvt_pk_bf16_f32 v67, v74, v75
	v_max_f32_e32 v56, 0, v56
	v_max_f32_e32 v57, 0, v57
	global_store_dwordx4 v[76:77], v[64:67], off offset:256
	s_nop 1
	v_pk_mul_f32 v[64:65], v[56:57], v[56:57]
	v_max_f32_e32 v60, 0, v60
	v_max_f32_e32 v61, 0, v61
	v_max_f32_e32 v58, 0, v58
	v_pk_mul_f32 v[60:61], v[60:61], v[60:61]
	v_max_f32_e32 v56, 0, v62
	v_max_f32_e32 v57, 0, v63
	v_max_f32_e32 v59, 0, v59
	s_mov_b32 s53, 0x100000
	v_pk_mul_f32 v[62:63], v[56:57], v[56:57]
	v_pk_mul_f32 v[66:67], v[58:59], v[58:59]
	v_cvt_pk_bf16_f32 v56, v60, v61
	v_add_co_u32_e32 v60, vcc, s53, v138
	v_cvt_pk_bf16_f32 v57, v62, v63
	v_cvt_pk_bf16_f32 v58, v64, v65
	v_cvt_pk_bf16_f32 v59, v66, v67
	v_addc_co_u32_e32 v61, vcc, 0, v139, vcc
	v_max_f32_e32 v48, 0, v48
	v_max_f32_e32 v49, 0, v49
	global_store_dwordx4 v[60:61], v[56:59], off
	s_nop 1
	v_pk_mul_f32 v[56:57], v[48:49], v[48:49]
	v_max_f32_e32 v50, 0, v50
	v_max_f32_e32 v52, 0, v52
	v_max_f32_e32 v53, 0, v53
	v_max_f32_e32 v48, 0, v54
	v_max_f32_e32 v49, 0, v55
	v_max_f32_e32 v51, 0, v51
	v_pk_mul_f32 v[52:53], v[52:53], v[52:53]
	v_pk_mul_f32 v[54:55], v[48:49], v[48:49]
	v_pk_mul_f32 v[58:59], v[50:51], v[50:51]
	v_cvt_pk_bf16_f32 v48, v52, v53
	v_cvt_pk_bf16_f32 v49, v54, v55
	v_cvt_pk_bf16_f32 v50, v56, v57
	v_cvt_pk_bf16_f32 v51, v58, v59
	v_max_f32_e32 v40, 0, v40
	v_max_f32_e32 v41, 0, v41
	global_store_dwordx4 v[60:61], v[48:51], off offset:256
	s_nop 1
	v_pk_mul_f32 v[48:49], v[40:41], v[40:41]
	v_max_f32_e32 v44, 0, v44
	v_max_f32_e32 v45, 0, v45
	v_max_f32_e32 v42, 0, v42
	v_pk_mul_f32 v[44:45], v[44:45], v[44:45]
	v_max_f32_e32 v40, 0, v46
	v_max_f32_e32 v41, 0, v47
	v_max_f32_e32 v43, 0, v43
	s_mov_b32 s53, 0x120000
	v_pk_mul_f32 v[46:47], v[40:41], v[40:41]
	v_pk_mul_f32 v[50:51], v[42:43], v[42:43]
	v_cvt_pk_bf16_f32 v40, v44, v45
	v_add_co_u32_e32 v44, vcc, s53, v138
	v_cvt_pk_bf16_f32 v41, v46, v47
	v_cvt_pk_bf16_f32 v42, v48, v49
	v_cvt_pk_bf16_f32 v43, v50, v51
	v_addc_co_u32_e32 v45, vcc, 0, v139, vcc
	v_max_f32_e32 v32, 0, v32
	v_max_f32_e32 v33, 0, v33
	global_store_dwordx4 v[44:45], v[40:43], off
	s_nop 1
	v_pk_mul_f32 v[40:41], v[32:33], v[32:33]
	v_max_f32_e32 v34, 0, v34
	v_max_f32_e32 v36, 0, v36
	v_max_f32_e32 v37, 0, v37
	v_max_f32_e32 v32, 0, v38
	v_max_f32_e32 v33, 0, v39
	v_max_f32_e32 v35, 0, v35
	v_pk_mul_f32 v[36:37], v[36:37], v[36:37]
	v_pk_mul_f32 v[38:39], v[32:33], v[32:33]
	v_pk_mul_f32 v[42:43], v[34:35], v[34:35]
	v_cvt_pk_bf16_f32 v32, v36, v37
	v_cvt_pk_bf16_f32 v33, v38, v39
	v_cvt_pk_bf16_f32 v34, v40, v41
	v_cvt_pk_bf16_f32 v35, v42, v43
	v_max_f32_e32 v24, 0, v24
	v_max_f32_e32 v25, 0, v25
	global_store_dwordx4 v[44:45], v[32:35], off offset:256
	s_nop 1
	v_pk_mul_f32 v[32:33], v[24:25], v[24:25]
	v_max_f32_e32 v28, 0, v28
	v_max_f32_e32 v29, 0, v29
	v_max_f32_e32 v26, 0, v26
	v_pk_mul_f32 v[28:29], v[28:29], v[28:29]
	v_max_f32_e32 v24, 0, v30
	v_max_f32_e32 v25, 0, v31
	v_max_f32_e32 v27, 0, v27
	s_mov_b32 s53, 0x140000
	v_pk_mul_f32 v[30:31], v[24:25], v[24:25]
	v_pk_mul_f32 v[34:35], v[26:27], v[26:27]
	v_cvt_pk_bf16_f32 v24, v28, v29
	v_add_co_u32_e32 v28, vcc, s53, v138
	v_cvt_pk_bf16_f32 v25, v30, v31
	v_cvt_pk_bf16_f32 v26, v32, v33
	v_cvt_pk_bf16_f32 v27, v34, v35
	v_addc_co_u32_e32 v29, vcc, 0, v139, vcc
	v_max_f32_e32 v16, 0, v16
	v_max_f32_e32 v17, 0, v17
	global_store_dwordx4 v[28:29], v[24:27], off
	s_nop 1
	v_pk_mul_f32 v[24:25], v[16:17], v[16:17]
	v_max_f32_e32 v18, 0, v18
	v_max_f32_e32 v20, 0, v20
	v_max_f32_e32 v21, 0, v21
	v_max_f32_e32 v16, 0, v22
	v_max_f32_e32 v17, 0, v23
	v_max_f32_e32 v19, 0, v19
	v_pk_mul_f32 v[20:21], v[20:21], v[20:21]
	v_pk_mul_f32 v[22:23], v[16:17], v[16:17]
	v_pk_mul_f32 v[26:27], v[18:19], v[18:19]
	v_cvt_pk_bf16_f32 v16, v20, v21
	v_cvt_pk_bf16_f32 v17, v22, v23
	v_cvt_pk_bf16_f32 v18, v24, v25
	v_cvt_pk_bf16_f32 v19, v26, v27
	v_max_f32_e32 v8, 0, v8
	v_max_f32_e32 v9, 0, v9
	global_store_dwordx4 v[28:29], v[16:19], off offset:256
	s_nop 1
	v_pk_mul_f32 v[16:17], v[8:9], v[8:9]
	v_max_f32_e32 v12, 0, v12
	v_max_f32_e32 v13, 0, v13
	v_max_f32_e32 v10, 0, v10
	v_pk_mul_f32 v[12:13], v[12:13], v[12:13]
	v_max_f32_e32 v8, 0, v14
	v_max_f32_e32 v9, 0, v15
	v_max_f32_e32 v11, 0, v11
	s_mov_b32 s53, 0x160000
	v_pk_mul_f32 v[14:15], v[8:9], v[8:9]
	v_pk_mul_f32 v[18:19], v[10:11], v[10:11]
	v_cvt_pk_bf16_f32 v8, v12, v13
	v_add_co_u32_e32 v12, vcc, s53, v138
	v_cvt_pk_bf16_f32 v9, v14, v15
	v_cvt_pk_bf16_f32 v10, v16, v17
	v_cvt_pk_bf16_f32 v11, v18, v19
	v_addc_co_u32_e32 v13, vcc, 0, v139, vcc
	v_max_f32_e32 v0, 0, v0
	v_max_f32_e32 v1, 0, v1
	global_store_dwordx4 v[12:13], v[8:11], off
	s_nop 1
	v_pk_mul_f32 v[8:9], v[0:1], v[0:1]
	v_max_f32_e32 v2, 0, v2
	v_max_f32_e32 v4, 0, v4
	v_max_f32_e32 v5, 0, v5
	v_max_f32_e32 v0, 0, v6
	v_max_f32_e32 v1, 0, v7
	v_max_f32_e32 v3, 0, v3
	v_pk_mul_f32 v[4:5], v[4:5], v[4:5]
	v_pk_mul_f32 v[6:7], v[0:1], v[0:1]
	v_pk_mul_f32 v[10:11], v[2:3], v[2:3]
	v_cvt_pk_bf16_f32 v0, v4, v5
	v_cvt_pk_bf16_f32 v1, v6, v7
	v_cvt_pk_bf16_f32 v2, v8, v9
	v_cvt_pk_bf16_f32 v3, v10, v11
	s_andn2_b64 vcc, exec, s[44:45]
	s_mov_b64 s[44:45], -1
	global_store_dwordx4 v[12:13], v[0:3], off offset:256
	s_cbranch_vccnz .LBB0_1621
	s_andn2_b64 vcc, exec, s[36:37]
	s_cbranch_vccnz .LBB0_1620
	s_barrier
	s_branch .LBB0_1620
